# rownorm prompt loop hand-written: gpost/gpre hoisted into registers, 4 rows of loads in flight per wave, no in-loop table round trips
# speedup vs baseline: 1.0157x; 1.0150x over previous
; __device__ __forceinline__ void rn_load(RowRegs& R, const float* base, const bf16_t* y, int lane) {
; #pragma unroll
;     for (int j = 0; j < 2; ++j) { R.v[2 * j] = __builtin_nontemporal_load((const f32x4*)(base + 512 * j + 8 * lane)); R.v[2 * j + 1] = __builtin_nontemporal_load((const f32x4*)(base + 512 * j + 8 * lane + 4)); if (y) R.y[j] = __builtin_nontemporal_load((const u32x4*)(y + 512 * j + 8 * lane)); }
; }
; __device__ __forceinline__ void phase_rownorm(ArgsK& a, int idx, int bid, int G, int tid, int wave, int lane, unsigned* cnt) {
;     const int layer = idx / 3, k = idx % 3; const float* ng = a.in[7] + (size_t)layer * 6 * DM;
;     const float* gpost = ng + (2 * k + 1) * DM; const float scale = (k == 1) ? 1.0f : 0.5f;
;     const float* gpre = (k < 2) ? ng + (2 * k + 2) * DM : (layer == 0 ? a.in[7] + 6 * DM : nullptr);
;     float* X = a.out; const bf16_t* Y = (const bf16_t*)(a.ws + WS_Y); bf16_t* HN = (bf16_t*)(a.ws + WS_HN);
;     if (bid < N_TAIL) return;
;     const int gw = (bid - N_TAIL) * 8 + wave, NGW = (G - N_TAIL) * 8;
;     for (int m = gw; m < MP; m += 2 * NGW) {
;         const int m2 = m + NGW; const bool two = m2 < MP;
;         const float* b0 = (idx == 0) ? a.in[0] + (size_t)m * DM : X + (size_t)m * DM;
;         const float* b1 = (idx == 0) ? a.in[0] + (size_t)m2 * DM : X + (size_t)m2 * DM;
;         RowRegs R0, R1; rn_load(R0, b0, Y + (size_t)m * DM, lane); if (two) rn_load(R1, b1, Y + (size_t)m2 * DM, lane);
;         rn_finish(R0, true, gpost, scale, X + (size_t)m * DM, gpre, gpre ? HN + (size_t)m * DM : nullptr, lane);
;         if (two) rn_finish(R1, true, gpost, scale, X + (size_t)m2 * DM, gpre, gpre ? HN + (size_t)m2 * DM : nullptr, lane); }
.LBB0_640:
	s_andn2_b64 vcc, exec, s[2:3]
	s_cbranch_vccnz .LBB0_679
	v_readlane_b32 s5, v254, 14
	s_add_i32 s4, s5, -3
	s_and_b64 s[2:3], s[44:45], exec
	s_load_dwordx2 s[2:3], s[38:39], 0x38
	s_load_dwordx2 s[16:17], s[38:39], 0xf0
	s_cselect_b32 s6, s5, s4
	v_readlane_b32 s4, v254, 15
	v_readlane_b32 s5, v254, 16
	s_lshl_b64 s[4:5], s[4:5], 2
	s_waitcnt lgkmcnt(0)
	s_add_u32 s7, s2, s4
	s_addc_u32 s8, s3, s5
	s_lshl_b32 s12, s6, 11
	s_lshl_b64 s[4:5], s[12:13], 2
	s_add_u32 s7, s7, s4
	s_addc_u32 s8, s8, s5
	s_add_u32 s10, s7, 0x1000
	s_addc_u32 s11, s8, 0
	s_cmp_eq_u32 s6, 1
	s_cselect_b64 s[4:5], -1, 0
	s_waitcnt vmcnt(0)
	v_cndmask_b32_e64 v69, 0.5, 1.0, s[4:5]
	s_add_u32 s4, s7, 0x2000
	s_addc_u32 s5, s8, 0
	s_add_u32 s7, s2, 0x6000
	s_addc_u32 s8, s3, 0
	s_and_b64 s[2:3], s[44:45], exec
	s_cselect_b32 s2, s7, 0
	s_cselect_b32 s3, s8, 0
	s_cmp_lt_u32 s6, 2
	s_cselect_b32 s3, s5, s3
	s_cselect_b32 s2, s4, s2
	s_add_u32 s8, s40, 0x6000000
	s_addc_u32 s9, s41, 0
	s_add_i32 s12, s77, -8
	s_lshl_b32 s4, s12, 3
	v_readlane_b32 s5, v254, 13
	s_add_i32 s24, s4, s5
	s_cmp_gt_i32 s24, 0xffff
	v_lshlrev_b32_e32 v50, 4, v158
	v_lshlrev_b32_e32 v0, 5, v158
	s_cbranch_scc1 .LBB0_655
	s_load_dwordx2 s[4:5], s[38:39], 0x0
	s_sub_i32 s44, s62, 64
	s_cmp_lg_u64 s[2:3], 0
	s_cselect_b64 s[40:41], -1, 0
	s_cmp_lg_u64 s[16:17], 0
	s_cselect_b64 s[42:43], -1, 0
	s_and_b64 s[6:7], s[46:47], exec
	v_mov_b32_e32 v51, v1
	s_waitcnt lgkmcnt(0)
	s_cselect_b32 s5, s5, s17
	s_cselect_b32 s4, s4, s16
	v_lshl_add_u64 v[52:53], s[0:1], 0, v[50:51]
	v_lshl_add_u64 v[54:55], s[10:11], 0, v[0:1]
	v_lshl_add_u64 v[56:57], s[16:17], 0, v[0:1]
	v_lshl_add_u64 v[58:59], s[2:3], 0, v[0:1]
	v_lshl_add_u64 v[60:61], s[8:9], 0, v[50:51]
	v_lshl_add_u64 v[62:63], s[4:5], 0, v[0:1]
	s_mov_b32 s19, 0
	s_mov_b32 s29, 0
	s_mov_b32 s35, 0
	s_mov_b32 s5, 0
	global_load_dwordx4 v[96:99], v[54:55], off offset:0
	global_load_dwordx4 v[100:103], v[54:55], off offset:16
	global_load_dwordx4 v[104:107], v[54:55], off offset:2048
	global_load_dwordx4 v[108:111], v[54:55], off offset:2064
	s_andn2_b64 vcc, exec, s[40:41]
	s_cbranch_vccnz .Lrn_nogpre
	global_load_dwordx4 v[112:115], v[58:59], off offset:0
	global_load_dwordx4 v[116:119], v[58:59], off offset:16
	global_load_dwordx4 v[120:123], v[58:59], off offset:2048
	global_load_dwordx4 v[124:127], v[58:59], off offset:2064
.Lrn_nogpre:
	s_mov_b32 s25, s24
	s_lshl_b32 s34, s25, 12
	s_lshl_b32 s4, s25, 11
	v_lshl_add_u64 v[228:229], v[62:63], 0, s[34:35]
	v_lshl_add_u64 v[230:231], v[52:53], 0, s[4:5]
	global_load_dwordx4 v[2:5], v[228:229], off nt
	global_load_dwordx4 v[6:9], v[228:229], off offset:16 nt
	global_load_dwordx4 v[10:13], v[228:229], off offset:2048 nt
	global_load_dwordx4 v[14:17], v[228:229], off offset:2064 nt
	global_load_dwordx4 v[18:21], v[230:231], off nt
	global_load_dwordx4 v[22:25], v[230:231], off offset:1024 nt
	s_add_i32 s25, s25, s44
	s_cmp_lt_i32 s25, 0x10000
	s_cselect_b32 s25, s25, s24
	s_lshl_b32 s34, s25, 12
	s_lshl_b32 s4, s25, 11
	v_lshl_add_u64 v[228:229], v[62:63], 0, s[34:35]
	v_lshl_add_u64 v[230:231], v[52:53], 0, s[4:5]
	global_load_dwordx4 v[26:29], v[228:229], off nt
	global_load_dwordx4 v[30:33], v[228:229], off offset:16 nt
	global_load_dwordx4 v[34:37], v[228:229], off offset:2048 nt
	global_load_dwordx4 v[38:41], v[228:229], off offset:2064 nt
	global_load_dwordx4 v[42:45], v[230:231], off nt
	global_load_dwordx4 v[46:49], v[230:231], off offset:1024 nt
	s_add_i32 s25, s25, s44
	s_cmp_lt_i32 s25, 0x10000
	s_cselect_b32 s25, s25, s24
	s_lshl_b32 s34, s25, 12
	s_lshl_b32 s4, s25, 11
	v_lshl_add_u64 v[228:229], v[62:63], 0, s[34:35]
	v_lshl_add_u64 v[230:231], v[52:53], 0, s[4:5]
	global_load_dwordx4 v[70:73], v[228:229], off nt
	global_load_dwordx4 v[74:77], v[228:229], off offset:16 nt
	global_load_dwordx4 v[78:81], v[228:229], off offset:2048 nt
	global_load_dwordx4 v[82:85], v[228:229], off offset:2064 nt
	global_load_dwordx4 v[86:89], v[230:231], off nt
	global_load_dwordx4 v[90:93], v[230:231], off offset:1024 nt
	s_waitcnt vmcnt(0)
.Lrn_loop:
	s_mul_i32 s25, s44, 3
	s_add_i32 s25, s25, s24
	s_cmp_lt_i32 s25, 0x10000
	s_cselect_b32 s25, s25, s24
	s_lshl_b32 s34, s25, 12
	s_lshl_b32 s4, s25, 11
	v_lshl_add_u64 v[228:229], v[62:63], 0, s[34:35]
	v_lshl_add_u64 v[230:231], v[52:53], 0, s[4:5]
	global_load_dwordx4 v[162:165], v[228:229], off nt
	global_load_dwordx4 v[166:169], v[228:229], off offset:16 nt
	global_load_dwordx4 v[170:173], v[228:229], off offset:2048 nt
	global_load_dwordx4 v[174:177], v[228:229], off offset:2064 nt
	global_load_dwordx4 v[178:181], v[230:231], off nt
	global_load_dwordx4 v[182:185], v[230:231], off offset:1024 nt
	s_lshl_b32 s18, s24, 12
	s_lshl_b32 s28, s24, 11
	s_andn2_b64 vcc, exec, s[40:41]
	s_waitcnt vmcnt(30)
; __device__ __forceinline__ unsigned cvt_pk_bf16(float lo, float hi) { unsigned r; asm volatile("v_cvt_pk_bf16_f32 %0, %1, %2" : "=v"(r) : "v"(lo), "v"(hi)); return r; }
; __device__ __forceinline__ float bf2f(unsigned short b) { return __uint_as_float(((unsigned)b) << 16); }
; __device__ __forceinline__ void rn_finish(RowRegs& R, bool hasy, const float* gpost, float scale, float* xo, const float* gpre, bf16_t* hn, int lane) {
;     if (hasy) { f32x4 t[4]; float s = 0.f;
; #pragma unroll
;         for (int j = 0; j < 2; ++j) { const u32x4 w = R.y[j];
;             t[2 * j] = (f32x4){bf2f(w.x & 0xffff), bf2f(w.x >> 16), bf2f(w.y & 0xffff), bf2f(w.y >> 16)}; t[2 * j + 1] = (f32x4){bf2f(w.z & 0xffff), bf2f(w.z >> 16), bf2f(w.w & 0xffff), bf2f(w.w >> 16)}; }
; #pragma unroll
;         for (int j = 0; j < 4; ++j) s += (t[j][0] * t[j][0] + t[j][1] * t[j][1]) + (t[j][2] * t[j][2] + t[j][3] * t[j][3]);
;         const float rs = rsqrtf(wave_sum(s) * (1.f / DM) + 1e-6f) * scale;
; #pragma unroll
;         for (int j = 0; j < 4; ++j) { const f32x4 g = *(const f32x4*)(gpost + 512 * (j >> 1) + 8 * lane + 4 * (j & 1)); R.v[j] = R.v[j] + t[j] * g * rs; } }
;     if (xo) {
; #pragma unroll
;         for (int j = 0; j < 4; ++j) __builtin_nontemporal_store(R.v[j], (f32x4*)(xo + 512 * (j >> 1) + 8 * lane + 4 * (j & 1))); }
;     if (hn) { float s = 0.f;
; #pragma unroll
;         for (int j = 0; j < 4; ++j) s += (R.v[j][0] * R.v[j][0] + R.v[j][1] * R.v[j][1]) + (R.v[j][2] * R.v[j][2] + R.v[j][3] * R.v[j][3]);
;         const float rs = rsqrtf(wave_sum(s) * (1.f / DM) + 1e-6f);
; #pragma unroll
;         for (int j = 0; j < 2; ++j) { const f32x4 g0 = *(const f32x4*)(gpre + 512 * j + 8 * lane), g1 = *(const f32x4*)(gpre + 512 * j + 8 * lane + 4); const f32x4 o0 = R.v[2 * j] * g0 * rs, o1 = R.v[2 * j + 1] * g1 * rs;
;             u32x4 w; w.x = cvt_pk_bf16(o0[0], o0[1]); w.y = cvt_pk_bf16(o0[2], o0[3]); w.z = cvt_pk_bf16(o1[0], o1[1]); w.w = cvt_pk_bf16(o1[2], o1[3]); *(u32x4*)(hn + 512 * j + 8 * lane) = w; } }
; }
	v_lshlrev_b32_e32 v206, 16, v18
	v_and_b32_e32 v207, 0xffff0000, v18
	v_lshlrev_b32_e32 v208, 16, v19
	v_and_b32_e32 v209, 0xffff0000, v19
	v_lshlrev_b32_e32 v210, 16, v20
	v_and_b32_e32 v211, 0xffff0000, v20
	v_lshlrev_b32_e32 v212, 16, v21
	v_and_b32_e32 v213, 0xffff0000, v21
	v_lshlrev_b32_e32 v214, 16, v22
	v_and_b32_e32 v215, 0xffff0000, v22
	v_lshlrev_b32_e32 v216, 16, v23
	v_and_b32_e32 v217, 0xffff0000, v23
	v_lshlrev_b32_e32 v218, 16, v24
	v_and_b32_e32 v219, 0xffff0000, v24
	v_lshlrev_b32_e32 v220, 16, v25
	v_and_b32_e32 v221, 0xffff0000, v25
	v_pk_mul_f32 v[222:223], v[206:207], v[206:207]
	v_pk_fma_f32 v[222:223], v[208:209], v[208:209], v[222:223]
	v_pk_fma_f32 v[222:223], v[210:211], v[210:211], v[222:223]
	v_pk_fma_f32 v[222:223], v[212:213], v[212:213], v[222:223]
	v_pk_fma_f32 v[222:223], v[214:215], v[214:215], v[222:223]
	v_pk_fma_f32 v[222:223], v[216:217], v[216:217], v[222:223]
	v_pk_fma_f32 v[222:223], v[218:219], v[218:219], v[222:223]
	v_pk_fma_f32 v[222:223], v[220:221], v[220:221], v[222:223]
	v_lshl_add_u64 v[228:229], v[56:57], 0, s[18:19]
	v_add_f32_e32 v224, v222, v223
	s_nop 1
	v_add_f32_dpp v224, v224, v224 quad_perm:[1,0,3,2] row_mask:0xf bank_mask:0xf bound_ctrl:1
	s_nop 1
	v_add_f32_dpp v224, v224, v224 quad_perm:[2,3,0,1] row_mask:0xf bank_mask:0xf bound_ctrl:1
	s_nop 1
	v_add_f32_dpp v224, v224, v224 row_half_mirror row_mask:0xf bank_mask:0xf bound_ctrl:1
	s_nop 1
	v_add_f32_dpp v224, v224, v224 row_mirror row_mask:0xf bank_mask:0xf bound_ctrl:1
	v_mov_b32_e32 v225, v224
	s_nop 1
	v_permlane16_swap_b32_e32 v224, v225
	v_add_f32_e32 v224, v224, v225
	v_mov_b32_e32 v225, v224
	s_nop 1
	v_permlane32_swap_b32_e32 v224, v225
	v_add_f32_e32 v224, v224, v225
	v_fmamk_f32 v224, v224, 0x3a800000, v197
	v_rsq_f32_e32 v224, v224
	v_lshl_add_u64 v[230:231], v[60:61], 0, s[28:29]
	v_mul_f32_e32 v226, v69, v224
	v_pk_mul_f32 v[206:207], v[206:207], v[96:97]
	v_pk_mul_f32 v[208:209], v[208:209], v[98:99]
	v_pk_mul_f32 v[210:211], v[210:211], v[100:101]
	v_pk_mul_f32 v[212:213], v[212:213], v[102:103]
	v_pk_mul_f32 v[214:215], v[214:215], v[104:105]
	v_pk_mul_f32 v[216:217], v[216:217], v[106:107]
	v_pk_mul_f32 v[218:219], v[218:219], v[108:109]
	v_pk_mul_f32 v[220:221], v[220:221], v[110:111]
	v_pk_fma_f32 v[2:3], v[206:207], v[226:227], v[2:3] op_sel_hi:[1,0,1]
	v_pk_fma_f32 v[4:5], v[208:209], v[226:227], v[4:5] op_sel_hi:[1,0,1]
	v_pk_fma_f32 v[6:7], v[210:211], v[226:227], v[6:7] op_sel_hi:[1,0,1]
	v_pk_fma_f32 v[8:9], v[212:213], v[226:227], v[8:9] op_sel_hi:[1,0,1]
	v_pk_fma_f32 v[10:11], v[214:215], v[226:227], v[10:11] op_sel_hi:[1,0,1]
	v_pk_fma_f32 v[12:13], v[216:217], v[226:227], v[12:13] op_sel_hi:[1,0,1]
	v_pk_fma_f32 v[14:15], v[218:219], v[226:227], v[14:15] op_sel_hi:[1,0,1]
	v_pk_fma_f32 v[16:17], v[220:221], v[226:227], v[16:17] op_sel_hi:[1,0,1]
	global_store_dwordx4 v[228:229], v[2:5], off nt
	global_store_dwordx4 v[228:229], v[6:9], off offset:16 nt
	global_store_dwordx4 v[228:229], v[10:13], off offset:2048 nt
	global_store_dwordx4 v[228:229], v[14:17], off offset:2064 nt
	s_cbranch_vccnz .Lrn_skip0
	v_pk_mul_f32 v[222:223], v[2:3], v[2:3]
	v_pk_fma_f32 v[222:223], v[4:5], v[4:5], v[222:223]
	v_pk_fma_f32 v[222:223], v[6:7], v[6:7], v[222:223]
	v_pk_fma_f32 v[222:223], v[8:9], v[8:9], v[222:223]
	v_pk_fma_f32 v[222:223], v[10:11], v[10:11], v[222:223]
	v_pk_fma_f32 v[222:223], v[12:13], v[12:13], v[222:223]
	v_pk_fma_f32 v[222:223], v[14:15], v[14:15], v[222:223]
	v_pk_fma_f32 v[222:223], v[16:17], v[16:17], v[222:223]
	v_pk_mul_f32 v[232:233], v[2:3], v[112:113]
	v_pk_mul_f32 v[234:235], v[4:5], v[114:115]
	v_pk_mul_f32 v[236:237], v[6:7], v[116:117]
	v_pk_mul_f32 v[238:239], v[8:9], v[118:119]
	v_pk_mul_f32 v[240:241], v[10:11], v[120:121]
	v_pk_mul_f32 v[242:243], v[12:13], v[122:123]
	v_pk_mul_f32 v[244:245], v[14:15], v[124:125]
	v_pk_mul_f32 v[246:247], v[16:17], v[126:127]
	v_add_f32_e32 v224, v222, v223
	s_nop 1
	v_add_f32_dpp v224, v224, v224 quad_perm:[1,0,3,2] row_mask:0xf bank_mask:0xf bound_ctrl:1
	s_nop 1
	v_add_f32_dpp v224, v224, v224 quad_perm:[2,3,0,1] row_mask:0xf bank_mask:0xf bound_ctrl:1
	s_nop 1
	v_add_f32_dpp v224, v224, v224 row_half_mirror row_mask:0xf bank_mask:0xf bound_ctrl:1
	s_nop 1
	v_add_f32_dpp v224, v224, v224 row_mirror row_mask:0xf bank_mask:0xf bound_ctrl:1
	v_mov_b32_e32 v225, v224
	s_nop 1
	v_permlane16_swap_b32_e32 v224, v225
	v_add_f32_e32 v224, v224, v225
	v_mov_b32_e32 v225, v224
	s_nop 1
	v_permlane32_swap_b32_e32 v224, v225
	v_add_f32_e32 v224, v224, v225
	v_fmamk_f32 v224, v224, 0x3a800000, v197
	v_rsq_f32_e32 v226, v224
	s_nop 0
	v_pk_mul_f32 v[232:233], v[232:233], v[226:227] op_sel_hi:[1,0]
	v_pk_mul_f32 v[234:235], v[234:235], v[226:227] op_sel_hi:[1,0]
	v_pk_mul_f32 v[236:237], v[236:237], v[226:227] op_sel_hi:[1,0]
	v_pk_mul_f32 v[238:239], v[238:239], v[226:227] op_sel_hi:[1,0]
	v_pk_mul_f32 v[240:241], v[240:241], v[226:227] op_sel_hi:[1,0]
	v_pk_mul_f32 v[242:243], v[242:243], v[226:227] op_sel_hi:[1,0]
	v_pk_mul_f32 v[244:245], v[244:245], v[226:227] op_sel_hi:[1,0]
	v_pk_mul_f32 v[246:247], v[246:247], v[226:227] op_sel_hi:[1,0]
	v_cvt_pk_bf16_f32 v248, v232, v233
	v_cvt_pk_bf16_f32 v249, v234, v235
	v_cvt_pk_bf16_f32 v250, v236, v237
	v_cvt_pk_bf16_f32 v251, v238, v239
	global_store_dwordx4 v[230:231], v[248:251], off
	s_nop 1
	v_cvt_pk_bf16_f32 v248, v240, v241
	v_cvt_pk_bf16_f32 v249, v242, v243
	v_cvt_pk_bf16_f32 v250, v244, v245
	v_cvt_pk_bf16_f32 v251, v246, v247
	global_store_dwordx4 v[230:231], v[248:251], off offset:1024
; __device__ __forceinline__ float bf2f(unsigned short b) { return __uint_as_float(((unsigned)b) << 16); }
; __device__ __forceinline__ void rn_finish(RowRegs& R, bool hasy, const float* gpost, float scale, float* xo, const float* gpre, bf16_t* hn, int lane) {
;     if (hasy) { f32x4 t[4]; float s = 0.f;
; #pragma unroll
;         for (int j = 0; j < 2; ++j) { const u32x4 w = R.y[j];
;             t[2 * j] = (f32x4){bf2f(w.x & 0xffff), bf2f(w.x >> 16), bf2f(w.y & 0xffff), bf2f(w.y >> 16)}; t[2 * j + 1] = (f32x4){bf2f(w.z & 0xffff), bf2f(w.z >> 16), bf2f(w.w & 0xffff), bf2f(w.w >> 16)}; }
; #pragma unroll
;         for (int j = 0; j < 4; ++j) s += (t[j][0] * t[j][0] + t[j][1] * t[j][1]) + (t[j][2] * t[j][2] + t[j][3] * t[j][3]);
;         const float rs = rsqrtf(wave_sum(s) * (1.f / DM) + 1e-6f) * scale;
; #pragma unroll
;         for (int j = 0; j < 4; ++j) { const f32x4 g = *(const f32x4*)(gpost + 512 * (j >> 1) + 8 * lane + 4 * (j & 1)); R.v[j] = R.v[j] + t[j] * g * rs; } }
;     if (xo) {
; #pragma unroll
;         for (int j = 0; j < 4; ++j) __builtin_nontemporal_store(R.v[j], (f32x4*)(xo + 512 * (j >> 1) + 8 * lane + 4 * (j & 1))); }
;     if (hn) { float s = 0.f;
; #pragma unroll
;         for (int j = 0; j < 4; ++j) s += (R.v[j][0] * R.v[j][0] + R.v[j][1] * R.v[j][1]) + (R.v[j][2] * R.v[j][2] + R.v[j][3] * R.v[j][3]);
;         const float rs = rsqrtf(wave_sum(s) * (1.f / DM) + 1e-6f);
; #pragma unroll
;         for (int j = 0; j < 2; ++j) { const f32x4 g0 = *(const f32x4*)(gpre + 512 * j + 8 * lane), g1 = *(const f32x4*)(gpre + 512 * j + 8 * lane + 4); const f32x4 o0 = R.v[2 * j] * g0 * rs, o1 = R.v[2 * j + 1] * g1 * rs;
;             u32x4 w; w.x = cvt_pk_bf16(o0[0], o0[1]); w.y = cvt_pk_bf16(o0[2], o0[3]); w.z = cvt_pk_bf16(o1[0], o1[1]); w.w = cvt_pk_bf16(o1[2], o1[3]); *(u32x4*)(hn + 512 * j + 8 * lane) = w; } }
; }
; __device__ __forceinline__ void phase_rownorm(ArgsK& a, int idx, int bid, int G, int tid, int wave, int lane, unsigned* cnt) {
;     ...
;     for (int m = gw; m < MP; m += 2 * NGW) {
;         const int m2 = m + NGW; const bool two = m2 < MP;
;         const float* b0 = (idx == 0) ? a.in[0] + (size_t)m * DM : X + (size_t)m * DM;
;         const float* b1 = (idx == 0) ? a.in[0] + (size_t)m2 * DM : X + (size_t)m2 * DM;
;         RowRegs R0, R1; rn_load(R0, b0, Y + (size_t)m * DM, lane); if (two) rn_load(R1, b1, Y + (size_t)m2 * DM, lane);
.Lrn_skip0:
	s_add_i32 s24, s24, s44
	s_cmp_gt_i32 s24, 0xffff
	s_cbranch_scc1 .Lrn_exit
	s_mul_i32 s25, s44, 3
	s_add_i32 s25, s25, s24
	s_cmp_lt_i32 s25, 0x10000
	s_cselect_b32 s25, s25, s24
	s_lshl_b32 s34, s25, 12
	s_lshl_b32 s4, s25, 11
	v_lshl_add_u64 v[228:229], v[62:63], 0, s[34:35]
	v_lshl_add_u64 v[230:231], v[52:53], 0, s[4:5]
	global_load_dwordx4 v[2:5], v[228:229], off nt
	global_load_dwordx4 v[6:9], v[228:229], off offset:16 nt
	global_load_dwordx4 v[10:13], v[228:229], off offset:2048 nt
	global_load_dwordx4 v[14:17], v[228:229], off offset:2064 nt
	global_load_dwordx4 v[18:21], v[230:231], off nt
	global_load_dwordx4 v[22:25], v[230:231], off offset:1024 nt
	s_lshl_b32 s18, s24, 12
	s_lshl_b32 s28, s24, 11
	s_andn2_b64 vcc, exec, s[40:41]
	s_waitcnt vmcnt(30)
	v_lshlrev_b32_e32 v206, 16, v42
	v_and_b32_e32 v207, 0xffff0000, v42
	v_lshlrev_b32_e32 v208, 16, v43
	v_and_b32_e32 v209, 0xffff0000, v43
	v_lshlrev_b32_e32 v210, 16, v44
	v_and_b32_e32 v211, 0xffff0000, v44
	v_lshlrev_b32_e32 v212, 16, v45
	v_and_b32_e32 v213, 0xffff0000, v45
	v_lshlrev_b32_e32 v214, 16, v46
	v_and_b32_e32 v215, 0xffff0000, v46
	v_lshlrev_b32_e32 v216, 16, v47
	v_and_b32_e32 v217, 0xffff0000, v47
	v_lshlrev_b32_e32 v218, 16, v48
	v_and_b32_e32 v219, 0xffff0000, v48
	v_lshlrev_b32_e32 v220, 16, v49
	v_and_b32_e32 v221, 0xffff0000, v49
	v_pk_mul_f32 v[222:223], v[206:207], v[206:207]
	v_pk_fma_f32 v[222:223], v[208:209], v[208:209], v[222:223]
	v_pk_fma_f32 v[222:223], v[210:211], v[210:211], v[222:223]
	v_pk_fma_f32 v[222:223], v[212:213], v[212:213], v[222:223]
	v_pk_fma_f32 v[222:223], v[214:215], v[214:215], v[222:223]
	v_pk_fma_f32 v[222:223], v[216:217], v[216:217], v[222:223]
	v_pk_fma_f32 v[222:223], v[218:219], v[218:219], v[222:223]
	v_pk_fma_f32 v[222:223], v[220:221], v[220:221], v[222:223]
	v_lshl_add_u64 v[228:229], v[56:57], 0, s[18:19]
	v_add_f32_e32 v224, v222, v223
	s_nop 1
	v_add_f32_dpp v224, v224, v224 quad_perm:[1,0,3,2] row_mask:0xf bank_mask:0xf bound_ctrl:1
	s_nop 1
	v_add_f32_dpp v224, v224, v224 quad_perm:[2,3,0,1] row_mask:0xf bank_mask:0xf bound_ctrl:1
	s_nop 1
	v_add_f32_dpp v224, v224, v224 row_half_mirror row_mask:0xf bank_mask:0xf bound_ctrl:1
	s_nop 1
	v_add_f32_dpp v224, v224, v224 row_mirror row_mask:0xf bank_mask:0xf bound_ctrl:1
	v_mov_b32_e32 v225, v224
	s_nop 1
	v_permlane16_swap_b32_e32 v224, v225
	v_add_f32_e32 v224, v224, v225
	v_mov_b32_e32 v225, v224
	s_nop 1
	v_permlane32_swap_b32_e32 v224, v225
	v_add_f32_e32 v224, v224, v225
	v_fmamk_f32 v224, v224, 0x3a800000, v197
	v_rsq_f32_e32 v224, v224
	v_lshl_add_u64 v[230:231], v[60:61], 0, s[28:29]
	v_mul_f32_e32 v226, v69, v224
	v_pk_mul_f32 v[206:207], v[206:207], v[96:97]
	v_pk_mul_f32 v[208:209], v[208:209], v[98:99]
	v_pk_mul_f32 v[210:211], v[210:211], v[100:101]
	v_pk_mul_f32 v[212:213], v[212:213], v[102:103]
	v_pk_mul_f32 v[214:215], v[214:215], v[104:105]
	v_pk_mul_f32 v[216:217], v[216:217], v[106:107]
	v_pk_mul_f32 v[218:219], v[218:219], v[108:109]
	v_pk_mul_f32 v[220:221], v[220:221], v[110:111]
	v_pk_fma_f32 v[26:27], v[206:207], v[226:227], v[26:27] op_sel_hi:[1,0,1]
	v_pk_fma_f32 v[28:29], v[208:209], v[226:227], v[28:29] op_sel_hi:[1,0,1]
	v_pk_fma_f32 v[30:31], v[210:211], v[226:227], v[30:31] op_sel_hi:[1,0,1]
	v_pk_fma_f32 v[32:33], v[212:213], v[226:227], v[32:33] op_sel_hi:[1,0,1]
	v_pk_fma_f32 v[34:35], v[214:215], v[226:227], v[34:35] op_sel_hi:[1,0,1]
	v_pk_fma_f32 v[36:37], v[216:217], v[226:227], v[36:37] op_sel_hi:[1,0,1]
	v_pk_fma_f32 v[38:39], v[218:219], v[226:227], v[38:39] op_sel_hi:[1,0,1]
	v_pk_fma_f32 v[40:41], v[220:221], v[226:227], v[40:41] op_sel_hi:[1,0,1]
	global_store_dwordx4 v[228:229], v[26:29], off nt
	global_store_dwordx4 v[228:229], v[30:33], off offset:16 nt
	global_store_dwordx4 v[228:229], v[34:37], off offset:2048 nt
	global_store_dwordx4 v[228:229], v[38:41], off offset:2064 nt
	s_cbranch_vccnz .Lrn_skip1
	v_pk_mul_f32 v[222:223], v[26:27], v[26:27]
	v_pk_fma_f32 v[222:223], v[28:29], v[28:29], v[222:223]
	v_pk_fma_f32 v[222:223], v[30:31], v[30:31], v[222:223]
	v_pk_fma_f32 v[222:223], v[32:33], v[32:33], v[222:223]
	v_pk_fma_f32 v[222:223], v[34:35], v[34:35], v[222:223]
	v_pk_fma_f32 v[222:223], v[36:37], v[36:37], v[222:223]
	v_pk_fma_f32 v[222:223], v[38:39], v[38:39], v[222:223]
	v_pk_fma_f32 v[222:223], v[40:41], v[40:41], v[222:223]
	v_pk_mul_f32 v[232:233], v[26:27], v[112:113]
	v_pk_mul_f32 v[234:235], v[28:29], v[114:115]
	v_pk_mul_f32 v[236:237], v[30:31], v[116:117]
	v_pk_mul_f32 v[238:239], v[32:33], v[118:119]
	v_pk_mul_f32 v[240:241], v[34:35], v[120:121]
	v_pk_mul_f32 v[242:243], v[36:37], v[122:123]
	v_pk_mul_f32 v[244:245], v[38:39], v[124:125]
	v_pk_mul_f32 v[246:247], v[40:41], v[126:127]
	v_add_f32_e32 v224, v222, v223
	s_nop 1
	v_add_f32_dpp v224, v224, v224 quad_perm:[1,0,3,2] row_mask:0xf bank_mask:0xf bound_ctrl:1
	s_nop 1
	v_add_f32_dpp v224, v224, v224 quad_perm:[2,3,0,1] row_mask:0xf bank_mask:0xf bound_ctrl:1
	s_nop 1
	v_add_f32_dpp v224, v224, v224 row_half_mirror row_mask:0xf bank_mask:0xf bound_ctrl:1
	s_nop 1
	v_add_f32_dpp v224, v224, v224 row_mirror row_mask:0xf bank_mask:0xf bound_ctrl:1
	v_mov_b32_e32 v225, v224
	s_nop 1
	v_permlane16_swap_b32_e32 v224, v225
	v_add_f32_e32 v224, v224, v225
	v_mov_b32_e32 v225, v224
	s_nop 1
	v_permlane32_swap_b32_e32 v224, v225
	v_add_f32_e32 v224, v224, v225
	v_fmamk_f32 v224, v224, 0x3a800000, v197
	v_rsq_f32_e32 v226, v224
	s_nop 0
	v_pk_mul_f32 v[232:233], v[232:233], v[226:227] op_sel_hi:[1,0]
	v_pk_mul_f32 v[234:235], v[234:235], v[226:227] op_sel_hi:[1,0]
	v_pk_mul_f32 v[236:237], v[236:237], v[226:227] op_sel_hi:[1,0]
	v_pk_mul_f32 v[238:239], v[238:239], v[226:227] op_sel_hi:[1,0]
	v_pk_mul_f32 v[240:241], v[240:241], v[226:227] op_sel_hi:[1,0]
	v_pk_mul_f32 v[242:243], v[242:243], v[226:227] op_sel_hi:[1,0]
	v_pk_mul_f32 v[244:245], v[244:245], v[226:227] op_sel_hi:[1,0]
	v_pk_mul_f32 v[246:247], v[246:247], v[226:227] op_sel_hi:[1,0]
	v_cvt_pk_bf16_f32 v248, v232, v233
	v_cvt_pk_bf16_f32 v249, v234, v235
	v_cvt_pk_bf16_f32 v250, v236, v237
	v_cvt_pk_bf16_f32 v251, v238, v239
	global_store_dwordx4 v[230:231], v[248:251], off
	s_nop 1
	v_cvt_pk_bf16_f32 v248, v240, v241
	v_cvt_pk_bf16_f32 v249, v242, v243
	v_cvt_pk_bf16_f32 v250, v244, v245
	v_cvt_pk_bf16_f32 v251, v246, v247
	global_store_dwordx4 v[230:231], v[248:251], off offset:1024
; __device__ __forceinline__ float bf2f(unsigned short b) { return __uint_as_float(((unsigned)b) << 16); }
; __device__ __forceinline__ void rn_finish(RowRegs& R, bool hasy, const float* gpost, float scale, float* xo, const float* gpre, bf16_t* hn, int lane) {
;     if (hasy) { f32x4 t[4]; float s = 0.f;
; #pragma unroll
;         for (int j = 0; j < 2; ++j) { const u32x4 w = R.y[j];
;             t[2 * j] = (f32x4){bf2f(w.x & 0xffff), bf2f(w.x >> 16), bf2f(w.y & 0xffff), bf2f(w.y >> 16)}; t[2 * j + 1] = (f32x4){bf2f(w.z & 0xffff), bf2f(w.z >> 16), bf2f(w.w & 0xffff), bf2f(w.w >> 16)}; }
; #pragma unroll
;         for (int j = 0; j < 4; ++j) s += (t[j][0] * t[j][0] + t[j][1] * t[j][1]) + (t[j][2] * t[j][2] + t[j][3] * t[j][3]);
;         const float rs = rsqrtf(wave_sum(s) * (1.f / DM) + 1e-6f) * scale;
; #pragma unroll
;         for (int j = 0; j < 4; ++j) { const f32x4 g = *(const f32x4*)(gpost + 512 * (j >> 1) + 8 * lane + 4 * (j & 1)); R.v[j] = R.v[j] + t[j] * g * rs; } }
;     if (xo) {
; #pragma unroll
;         for (int j = 0; j < 4; ++j) __builtin_nontemporal_store(R.v[j], (f32x4*)(xo + 512 * (j >> 1) + 8 * lane + 4 * (j & 1))); }
;     if (hn) { float s = 0.f;
; #pragma unroll
;         for (int j = 0; j < 4; ++j) s += (R.v[j][0] * R.v[j][0] + R.v[j][1] * R.v[j][1]) + (R.v[j][2] * R.v[j][2] + R.v[j][3] * R.v[j][3]);
;         const float rs = rsqrtf(wave_sum(s) * (1.f / DM) + 1e-6f);
; #pragma unroll
;         for (int j = 0; j < 2; ++j) { const f32x4 g0 = *(const f32x4*)(gpre + 512 * j + 8 * lane), g1 = *(const f32x4*)(gpre + 512 * j + 8 * lane + 4); const f32x4 o0 = R.v[2 * j] * g0 * rs, o1 = R.v[2 * j + 1] * g1 * rs;
;             u32x4 w; w.x = cvt_pk_bf16(o0[0], o0[1]); w.y = cvt_pk_bf16(o0[2], o0[3]); w.z = cvt_pk_bf16(o1[0], o1[1]); w.w = cvt_pk_bf16(o1[2], o1[3]); *(u32x4*)(hn + 512 * j + 8 * lane) = w; } }
; }
; __device__ __forceinline__ void phase_rownorm(ArgsK& a, int idx, int bid, int G, int tid, int wave, int lane, unsigned* cnt) {
;     ...
;     for (int m = gw; m < MP; m += 2 * NGW) {
;         const int m2 = m + NGW; const bool two = m2 < MP;
;         const float* b0 = (idx == 0) ? a.in[0] + (size_t)m * DM : X + (size_t)m * DM;
;         const float* b1 = (idx == 0) ? a.in[0] + (size_t)m2 * DM : X + (size_t)m2 * DM;
;         RowRegs R0, R1; rn_load(R0, b0, Y + (size_t)m * DM, lane); if (two) rn_load(R1, b1, Y + (size_t)m2 * DM, lane);
.Lrn_skip1:
	s_add_i32 s24, s24, s44
	s_cmp_gt_i32 s24, 0xffff
	s_cbranch_scc1 .Lrn_exit
	s_mul_i32 s25, s44, 3
	s_add_i32 s25, s25, s24
	s_cmp_lt_i32 s25, 0x10000
	s_cselect_b32 s25, s25, s24
	s_lshl_b32 s34, s25, 12
	s_lshl_b32 s4, s25, 11
	v_lshl_add_u64 v[228:229], v[62:63], 0, s[34:35]
	v_lshl_add_u64 v[230:231], v[52:53], 0, s[4:5]
	global_load_dwordx4 v[26:29], v[228:229], off nt
	global_load_dwordx4 v[30:33], v[228:229], off offset:16 nt
	global_load_dwordx4 v[34:37], v[228:229], off offset:2048 nt
	global_load_dwordx4 v[38:41], v[228:229], off offset:2064 nt
	global_load_dwordx4 v[42:45], v[230:231], off nt
	global_load_dwordx4 v[46:49], v[230:231], off offset:1024 nt
	s_lshl_b32 s18, s24, 12
	s_lshl_b32 s28, s24, 11
	s_andn2_b64 vcc, exec, s[40:41]
	s_waitcnt vmcnt(30)
	v_lshlrev_b32_e32 v206, 16, v86
	v_and_b32_e32 v207, 0xffff0000, v86
	v_lshlrev_b32_e32 v208, 16, v87
	v_and_b32_e32 v209, 0xffff0000, v87
	v_lshlrev_b32_e32 v210, 16, v88
	v_and_b32_e32 v211, 0xffff0000, v88
	v_lshlrev_b32_e32 v212, 16, v89
	v_and_b32_e32 v213, 0xffff0000, v89
	v_lshlrev_b32_e32 v214, 16, v90
	v_and_b32_e32 v215, 0xffff0000, v90
	v_lshlrev_b32_e32 v216, 16, v91
	v_and_b32_e32 v217, 0xffff0000, v91
	v_lshlrev_b32_e32 v218, 16, v92
	v_and_b32_e32 v219, 0xffff0000, v92
	v_lshlrev_b32_e32 v220, 16, v93
	v_and_b32_e32 v221, 0xffff0000, v93
	v_pk_mul_f32 v[222:223], v[206:207], v[206:207]
	v_pk_fma_f32 v[222:223], v[208:209], v[208:209], v[222:223]
	v_pk_fma_f32 v[222:223], v[210:211], v[210:211], v[222:223]
	v_pk_fma_f32 v[222:223], v[212:213], v[212:213], v[222:223]
	v_pk_fma_f32 v[222:223], v[214:215], v[214:215], v[222:223]
	v_pk_fma_f32 v[222:223], v[216:217], v[216:217], v[222:223]
	v_pk_fma_f32 v[222:223], v[218:219], v[218:219], v[222:223]
	v_pk_fma_f32 v[222:223], v[220:221], v[220:221], v[222:223]
	v_lshl_add_u64 v[228:229], v[56:57], 0, s[18:19]
	v_add_f32_e32 v224, v222, v223
	s_nop 1
	v_add_f32_dpp v224, v224, v224 quad_perm:[1,0,3,2] row_mask:0xf bank_mask:0xf bound_ctrl:1
	s_nop 1
	v_add_f32_dpp v224, v224, v224 quad_perm:[2,3,0,1] row_mask:0xf bank_mask:0xf bound_ctrl:1
	s_nop 1
	v_add_f32_dpp v224, v224, v224 row_half_mirror row_mask:0xf bank_mask:0xf bound_ctrl:1
	s_nop 1
	v_add_f32_dpp v224, v224, v224 row_mirror row_mask:0xf bank_mask:0xf bound_ctrl:1
	v_mov_b32_e32 v225, v224
	s_nop 1
	v_permlane16_swap_b32_e32 v224, v225
	v_add_f32_e32 v224, v224, v225
	v_mov_b32_e32 v225, v224
	s_nop 1
	v_permlane32_swap_b32_e32 v224, v225
	v_add_f32_e32 v224, v224, v225
	v_fmamk_f32 v224, v224, 0x3a800000, v197
	v_rsq_f32_e32 v224, v224
	v_lshl_add_u64 v[230:231], v[60:61], 0, s[28:29]
	v_mul_f32_e32 v226, v69, v224
	v_pk_mul_f32 v[206:207], v[206:207], v[96:97]
	v_pk_mul_f32 v[208:209], v[208:209], v[98:99]
	v_pk_mul_f32 v[210:211], v[210:211], v[100:101]
	v_pk_mul_f32 v[212:213], v[212:213], v[102:103]
	v_pk_mul_f32 v[214:215], v[214:215], v[104:105]
	v_pk_mul_f32 v[216:217], v[216:217], v[106:107]
	v_pk_mul_f32 v[218:219], v[218:219], v[108:109]
	v_pk_mul_f32 v[220:221], v[220:221], v[110:111]
	v_pk_fma_f32 v[70:71], v[206:207], v[226:227], v[70:71] op_sel_hi:[1,0,1]
	v_pk_fma_f32 v[72:73], v[208:209], v[226:227], v[72:73] op_sel_hi:[1,0,1]
	v_pk_fma_f32 v[74:75], v[210:211], v[226:227], v[74:75] op_sel_hi:[1,0,1]
	v_pk_fma_f32 v[76:77], v[212:213], v[226:227], v[76:77] op_sel_hi:[1,0,1]
	v_pk_fma_f32 v[78:79], v[214:215], v[226:227], v[78:79] op_sel_hi:[1,0,1]
	v_pk_fma_f32 v[80:81], v[216:217], v[226:227], v[80:81] op_sel_hi:[1,0,1]
	v_pk_fma_f32 v[82:83], v[218:219], v[226:227], v[82:83] op_sel_hi:[1,0,1]
	v_pk_fma_f32 v[84:85], v[220:221], v[226:227], v[84:85] op_sel_hi:[1,0,1]
	global_store_dwordx4 v[228:229], v[70:73], off nt
	global_store_dwordx4 v[228:229], v[74:77], off offset:16 nt
	global_store_dwordx4 v[228:229], v[78:81], off offset:2048 nt
	global_store_dwordx4 v[228:229], v[82:85], off offset:2064 nt
	s_cbranch_vccnz .Lrn_skip2
	v_pk_mul_f32 v[222:223], v[70:71], v[70:71]
	v_pk_fma_f32 v[222:223], v[72:73], v[72:73], v[222:223]
	v_pk_fma_f32 v[222:223], v[74:75], v[74:75], v[222:223]
	v_pk_fma_f32 v[222:223], v[76:77], v[76:77], v[222:223]
	v_pk_fma_f32 v[222:223], v[78:79], v[78:79], v[222:223]
	v_pk_fma_f32 v[222:223], v[80:81], v[80:81], v[222:223]
	v_pk_fma_f32 v[222:223], v[82:83], v[82:83], v[222:223]
	v_pk_fma_f32 v[222:223], v[84:85], v[84:85], v[222:223]
	v_pk_mul_f32 v[232:233], v[70:71], v[112:113]
	v_pk_mul_f32 v[234:235], v[72:73], v[114:115]
	v_pk_mul_f32 v[236:237], v[74:75], v[116:117]
	v_pk_mul_f32 v[238:239], v[76:77], v[118:119]
	v_pk_mul_f32 v[240:241], v[78:79], v[120:121]
	v_pk_mul_f32 v[242:243], v[80:81], v[122:123]
	v_pk_mul_f32 v[244:245], v[82:83], v[124:125]
	v_pk_mul_f32 v[246:247], v[84:85], v[126:127]
	v_add_f32_e32 v224, v222, v223
	s_nop 1
	v_add_f32_dpp v224, v224, v224 quad_perm:[1,0,3,2] row_mask:0xf bank_mask:0xf bound_ctrl:1
	s_nop 1
	v_add_f32_dpp v224, v224, v224 quad_perm:[2,3,0,1] row_mask:0xf bank_mask:0xf bound_ctrl:1
	s_nop 1
	v_add_f32_dpp v224, v224, v224 row_half_mirror row_mask:0xf bank_mask:0xf bound_ctrl:1
	s_nop 1
	v_add_f32_dpp v224, v224, v224 row_mirror row_mask:0xf bank_mask:0xf bound_ctrl:1
	v_mov_b32_e32 v225, v224
	s_nop 1
	v_permlane16_swap_b32_e32 v224, v225
	v_add_f32_e32 v224, v224, v225
	v_mov_b32_e32 v225, v224
	s_nop 1
	v_permlane32_swap_b32_e32 v224, v225
	v_add_f32_e32 v224, v224, v225
	v_fmamk_f32 v224, v224, 0x3a800000, v197
	v_rsq_f32_e32 v226, v224
	s_nop 0
	v_pk_mul_f32 v[232:233], v[232:233], v[226:227] op_sel_hi:[1,0]
	v_pk_mul_f32 v[234:235], v[234:235], v[226:227] op_sel_hi:[1,0]
	v_pk_mul_f32 v[236:237], v[236:237], v[226:227] op_sel_hi:[1,0]
	v_pk_mul_f32 v[238:239], v[238:239], v[226:227] op_sel_hi:[1,0]
	v_pk_mul_f32 v[240:241], v[240:241], v[226:227] op_sel_hi:[1,0]
	v_pk_mul_f32 v[242:243], v[242:243], v[226:227] op_sel_hi:[1,0]
	v_pk_mul_f32 v[244:245], v[244:245], v[226:227] op_sel_hi:[1,0]
	v_pk_mul_f32 v[246:247], v[246:247], v[226:227] op_sel_hi:[1,0]
	v_cvt_pk_bf16_f32 v248, v232, v233
	v_cvt_pk_bf16_f32 v249, v234, v235
	v_cvt_pk_bf16_f32 v250, v236, v237
	v_cvt_pk_bf16_f32 v251, v238, v239
	global_store_dwordx4 v[230:231], v[248:251], off
	s_nop 1
	v_cvt_pk_bf16_f32 v248, v240, v241
	v_cvt_pk_bf16_f32 v249, v242, v243
	v_cvt_pk_bf16_f32 v250, v244, v245
	v_cvt_pk_bf16_f32 v251, v246, v247
	global_store_dwordx4 v[230:231], v[248:251], off offset:1024
; __device__ __forceinline__ void rn_finish(RowRegs& R, bool hasy, const float* gpost, float scale, float* xo, const float* gpre, bf16_t* hn, int lane) {
;     if (hasy) { f32x4 t[4]; float s = 0.f;
; #pragma unroll
;         for (int j = 0; j < 2; ++j) { const u32x4 w = R.y[j];
;             t[2 * j] = (f32x4){bf2f(w.x & 0xffff), bf2f(w.x >> 16), bf2f(w.y & 0xffff), bf2f(w.y >> 16)}; t[2 * j + 1] = (f32x4){bf2f(w.z & 0xffff), bf2f(w.z >> 16), bf2f(w.w & 0xffff), bf2f(w.w >> 16)}; }
; #pragma unroll
;         for (int j = 0; j < 4; ++j) s += (t[j][0] * t[j][0] + t[j][1] * t[j][1]) + (t[j][2] * t[j][2] + t[j][3] * t[j][3]);
;         const float rs = rsqrtf(wave_sum(s) * (1.f / DM) + 1e-6f) * scale;
; #pragma unroll
;         for (int j = 0; j < 4; ++j) { const f32x4 g = *(const f32x4*)(gpost + 512 * (j >> 1) + 8 * lane + 4 * (j & 1)); R.v[j] = R.v[j] + t[j] * g * rs; } }
;     if (xo) {
; #pragma unroll
;         for (int j = 0; j < 4; ++j) __builtin_nontemporal_store(R.v[j], (f32x4*)(xo + 512 * (j >> 1) + 8 * lane + 4 * (j & 1))); }
;     if (hn) { float s = 0.f;
; #pragma unroll
;         for (int j = 0; j < 4; ++j) s += (R.v[j][0] * R.v[j][0] + R.v[j][1] * R.v[j][1]) + (R.v[j][2] * R.v[j][2] + R.v[j][3] * R.v[j][3]);
;         const float rs = rsqrtf(wave_sum(s) * (1.f / DM) + 1e-6f);
; #pragma unroll
;         for (int j = 0; j < 2; ++j) { const f32x4 g0 = *(const f32x4*)(gpre + 512 * j + 8 * lane), g1 = *(const f32x4*)(gpre + 512 * j + 8 * lane + 4); const f32x4 o0 = R.v[2 * j] * g0 * rs, o1 = R.v[2 * j + 1] * g1 * rs;
;             u32x4 w; w.x = cvt_pk_bf16(o0[0], o0[1]); w.y = cvt_pk_bf16(o0[2], o0[3]); w.z = cvt_pk_bf16(o1[0], o1[1]); w.w = cvt_pk_bf16(o1[2], o1[3]); *(u32x4*)(hn + 512 * j + 8 * lane) = w; } }
; }
; __device__ __forceinline__ void phase_rownorm(ArgsK& a, int idx, int bid, int G, int tid, int wave, int lane, unsigned* cnt) {
;     ...
;     if (bid < N_TAIL) return;
;     const int gw = (bid - N_TAIL) * 8 + wave, NGW = (G - N_TAIL) * 8;
;     for (int m = gw; m < MP; m += 2 * NGW) {
;         const int m2 = m + NGW; const bool two = m2 < MP;
;         const float* b0 = (idx == 0) ? a.in[0] + (size_t)m * DM : X + (size_t)m * DM;
;         const float* b1 = (idx == 0) ? a.in[0] + (size_t)m2 * DM : X + (size_t)m2 * DM;
;         RowRegs R0, R1; rn_load(R0, b0, Y + (size_t)m * DM, lane); if (two) rn_load(R1, b1, Y + (size_t)m2 * DM, lane);
.Lrn_skip2:
	s_add_i32 s24, s24, s44
	s_cmp_gt_i32 s24, 0xffff
	s_cbranch_scc1 .Lrn_exit
	s_mul_i32 s25, s44, 3
	s_add_i32 s25, s25, s24
	s_cmp_lt_i32 s25, 0x10000
	s_cselect_b32 s25, s25, s24
	s_lshl_b32 s34, s25, 12
	s_lshl_b32 s4, s25, 11
	v_lshl_add_u64 v[228:229], v[62:63], 0, s[34:35]
	v_lshl_add_u64 v[230:231], v[52:53], 0, s[4:5]
	global_load_dwordx4 v[70:73], v[228:229], off nt
	global_load_dwordx4 v[74:77], v[228:229], off offset:16 nt
	global_load_dwordx4 v[78:81], v[228:229], off offset:2048 nt
	global_load_dwordx4 v[82:85], v[228:229], off offset:2064 nt
	global_load_dwordx4 v[86:89], v[230:231], off nt
	global_load_dwordx4 v[90:93], v[230:231], off offset:1024 nt
	s_lshl_b32 s18, s24, 12
	s_lshl_b32 s28, s24, 11
	s_andn2_b64 vcc, exec, s[40:41]
	s_waitcnt vmcnt(30)
	v_lshlrev_b32_e32 v206, 16, v178
	v_and_b32_e32 v207, 0xffff0000, v178
	v_lshlrev_b32_e32 v208, 16, v179
	v_and_b32_e32 v209, 0xffff0000, v179
	v_lshlrev_b32_e32 v210, 16, v180
	v_and_b32_e32 v211, 0xffff0000, v180
	v_lshlrev_b32_e32 v212, 16, v181
	v_and_b32_e32 v213, 0xffff0000, v181
	v_lshlrev_b32_e32 v214, 16, v182
	v_and_b32_e32 v215, 0xffff0000, v182
	v_lshlrev_b32_e32 v216, 16, v183
	v_and_b32_e32 v217, 0xffff0000, v183
	v_lshlrev_b32_e32 v218, 16, v184
	v_and_b32_e32 v219, 0xffff0000, v184
	v_lshlrev_b32_e32 v220, 16, v185
	v_and_b32_e32 v221, 0xffff0000, v185
	v_pk_mul_f32 v[222:223], v[206:207], v[206:207]
	v_pk_fma_f32 v[222:223], v[208:209], v[208:209], v[222:223]
	v_pk_fma_f32 v[222:223], v[210:211], v[210:211], v[222:223]
	v_pk_fma_f32 v[222:223], v[212:213], v[212:213], v[222:223]
	v_pk_fma_f32 v[222:223], v[214:215], v[214:215], v[222:223]
	v_pk_fma_f32 v[222:223], v[216:217], v[216:217], v[222:223]
	v_pk_fma_f32 v[222:223], v[218:219], v[218:219], v[222:223]
	v_pk_fma_f32 v[222:223], v[220:221], v[220:221], v[222:223]
	v_lshl_add_u64 v[228:229], v[56:57], 0, s[18:19]
	v_add_f32_e32 v224, v222, v223
	s_nop 1
	v_add_f32_dpp v224, v224, v224 quad_perm:[1,0,3,2] row_mask:0xf bank_mask:0xf bound_ctrl:1
	s_nop 1
	v_add_f32_dpp v224, v224, v224 quad_perm:[2,3,0,1] row_mask:0xf bank_mask:0xf bound_ctrl:1
	s_nop 1
	v_add_f32_dpp v224, v224, v224 row_half_mirror row_mask:0xf bank_mask:0xf bound_ctrl:1
	s_nop 1
	v_add_f32_dpp v224, v224, v224 row_mirror row_mask:0xf bank_mask:0xf bound_ctrl:1
	v_mov_b32_e32 v225, v224
	s_nop 1
	v_permlane16_swap_b32_e32 v224, v225
	v_add_f32_e32 v224, v224, v225
	v_mov_b32_e32 v225, v224
	s_nop 1
	v_permlane32_swap_b32_e32 v224, v225
	v_add_f32_e32 v224, v224, v225
	v_fmamk_f32 v224, v224, 0x3a800000, v197
	v_rsq_f32_e32 v224, v224
	v_lshl_add_u64 v[230:231], v[60:61], 0, s[28:29]
	v_mul_f32_e32 v226, v69, v224
	v_pk_mul_f32 v[206:207], v[206:207], v[96:97]
	v_pk_mul_f32 v[208:209], v[208:209], v[98:99]
	v_pk_mul_f32 v[210:211], v[210:211], v[100:101]
	v_pk_mul_f32 v[212:213], v[212:213], v[102:103]
	v_pk_mul_f32 v[214:215], v[214:215], v[104:105]
	v_pk_mul_f32 v[216:217], v[216:217], v[106:107]
	v_pk_mul_f32 v[218:219], v[218:219], v[108:109]
	v_pk_mul_f32 v[220:221], v[220:221], v[110:111]
	v_pk_fma_f32 v[162:163], v[206:207], v[226:227], v[162:163] op_sel_hi:[1,0,1]
	v_pk_fma_f32 v[164:165], v[208:209], v[226:227], v[164:165] op_sel_hi:[1,0,1]
	v_pk_fma_f32 v[166:167], v[210:211], v[226:227], v[166:167] op_sel_hi:[1,0,1]
	v_pk_fma_f32 v[168:169], v[212:213], v[226:227], v[168:169] op_sel_hi:[1,0,1]
	v_pk_fma_f32 v[170:171], v[214:215], v[226:227], v[170:171] op_sel_hi:[1,0,1]
	v_pk_fma_f32 v[172:173], v[216:217], v[226:227], v[172:173] op_sel_hi:[1,0,1]
	v_pk_fma_f32 v[174:175], v[218:219], v[226:227], v[174:175] op_sel_hi:[1,0,1]
	v_pk_fma_f32 v[176:177], v[220:221], v[226:227], v[176:177] op_sel_hi:[1,0,1]
	global_store_dwordx4 v[228:229], v[162:165], off nt
	global_store_dwordx4 v[228:229], v[166:169], off offset:16 nt
	global_store_dwordx4 v[228:229], v[170:173], off offset:2048 nt
	global_store_dwordx4 v[228:229], v[174:177], off offset:2064 nt
	s_cbranch_vccnz .Lrn_skip3
	v_pk_mul_f32 v[222:223], v[162:163], v[162:163]
	v_pk_fma_f32 v[222:223], v[164:165], v[164:165], v[222:223]
	v_pk_fma_f32 v[222:223], v[166:167], v[166:167], v[222:223]
	v_pk_fma_f32 v[222:223], v[168:169], v[168:169], v[222:223]
	v_pk_fma_f32 v[222:223], v[170:171], v[170:171], v[222:223]
	v_pk_fma_f32 v[222:223], v[172:173], v[172:173], v[222:223]
	v_pk_fma_f32 v[222:223], v[174:175], v[174:175], v[222:223]
	v_pk_fma_f32 v[222:223], v[176:177], v[176:177], v[222:223]
	v_pk_mul_f32 v[232:233], v[162:163], v[112:113]
	v_pk_mul_f32 v[234:235], v[164:165], v[114:115]
	v_pk_mul_f32 v[236:237], v[166:167], v[116:117]
	v_pk_mul_f32 v[238:239], v[168:169], v[118:119]
	v_pk_mul_f32 v[240:241], v[170:171], v[120:121]
	v_pk_mul_f32 v[242:243], v[172:173], v[122:123]
	v_pk_mul_f32 v[244:245], v[174:175], v[124:125]
	v_pk_mul_f32 v[246:247], v[176:177], v[126:127]
	v_add_f32_e32 v224, v222, v223
	s_nop 1
	v_add_f32_dpp v224, v224, v224 quad_perm:[1,0,3,2] row_mask:0xf bank_mask:0xf bound_ctrl:1
	s_nop 1
	v_add_f32_dpp v224, v224, v224 quad_perm:[2,3,0,1] row_mask:0xf bank_mask:0xf bound_ctrl:1
	s_nop 1
	v_add_f32_dpp v224, v224, v224 row_half_mirror row_mask:0xf bank_mask:0xf bound_ctrl:1
	s_nop 1
	v_add_f32_dpp v224, v224, v224 row_mirror row_mask:0xf bank_mask:0xf bound_ctrl:1
	v_mov_b32_e32 v225, v224
	s_nop 1
	v_permlane16_swap_b32_e32 v224, v225
	v_add_f32_e32 v224, v224, v225
	v_mov_b32_e32 v225, v224
	s_nop 1
	v_permlane32_swap_b32_e32 v224, v225
	v_add_f32_e32 v224, v224, v225
	v_fmamk_f32 v224, v224, 0x3a800000, v197
	v_rsq_f32_e32 v226, v224
	s_nop 0
	v_pk_mul_f32 v[232:233], v[232:233], v[226:227] op_sel_hi:[1,0]
	v_pk_mul_f32 v[234:235], v[234:235], v[226:227] op_sel_hi:[1,0]
	v_pk_mul_f32 v[236:237], v[236:237], v[226:227] op_sel_hi:[1,0]
	v_pk_mul_f32 v[238:239], v[238:239], v[226:227] op_sel_hi:[1,0]
	v_pk_mul_f32 v[240:241], v[240:241], v[226:227] op_sel_hi:[1,0]
	v_pk_mul_f32 v[242:243], v[242:243], v[226:227] op_sel_hi:[1,0]
	v_pk_mul_f32 v[244:245], v[244:245], v[226:227] op_sel_hi:[1,0]
	v_pk_mul_f32 v[246:247], v[246:247], v[226:227] op_sel_hi:[1,0]
	v_cvt_pk_bf16_f32 v248, v232, v233
	v_cvt_pk_bf16_f32 v249, v234, v235
	v_cvt_pk_bf16_f32 v250, v236, v237
	v_cvt_pk_bf16_f32 v251, v238, v239
	global_store_dwordx4 v[230:231], v[248:251], off
	s_nop 1
	v_cvt_pk_bf16_f32 v248, v240, v241
	v_cvt_pk_bf16_f32 v249, v242, v243
	v_cvt_pk_bf16_f32 v250, v244, v245
	v_cvt_pk_bf16_f32 v251, v246, v247
	global_store_dwordx4 v[230:231], v[248:251], off offset:1024
.Lrn_skip3:
	s_add_i32 s24, s24, s44
	s_cmp_gt_i32 s24, 0xffff
	s_cbranch_scc1 .Lrn_exit
	s_branch .Lrn_loop
.Lrn_exit:
	s_waitcnt vmcnt(0)
.LBB0_655:
	s_load_dwordx2 s[40:41], s[38:39], 0xf8
	s_cmp_lt_i32 s77, 40
	s_cbranch_scc0 .LBB0_679
	v_cmp_eq_u32_e32 vcc, 0, v160
	s_and_saveexec_b64 s[4:5], vcc
	s_cbranch_execz .LBB0_669
	global_load_dword v2, v1, s[14:15] sc1
	s_waitcnt vmcnt(0)
	v_cmp_lt_u32_e32 vcc, 7, v2
	s_cbranch_vccnz .LBB0_668
	s_mov_b32 s18, 0x3ffff8
	s_branch .LBB0_660
